# v029
# speedup vs baseline: 1.0487x; 1.0294x over previous
; #define ISSUE_K(t, slot) do { const char* kg_ = (const char*)(Kh + (long)(t) * (KVBLK * 192)); char* kl_ = K_lds + (slot) * SHM_K + tid * 16; \
;     DMA16(kg_ + kso0, kl_); DMA16(kg_ + kso1, kl_ + 8192); DMA16(kg_ + kso2, kl_ + 16384); } while (0)
; #define ISSUE_V(t, slot) do { const char* vg_ = (const char*)(Vh + (long)(t) * (KVBLK * 128)); char* vl_ = V_lds + (slot) * SHM_V + tid * 16; \
;     DMA16(vg_ + vso0, vl_); DMA16(vg_ + vso1, vl_ + 8192); } while (0)
; #define TBAR(n) do { asm volatile("s_waitcnt vmcnt(" #n ") lgkmcnt(0)" ::: "memory"); __builtin_amdgcn_s_barrier(); SBAR(); } while (0)
; __device__ __forceinline__ void qkt(f32x16& p0, f32x16& p1, const char* Ks, const bf16x8* qr, int r32, int hi) {
;   p0 = f32x16{}; p1 = f32x16{};
; #pragma unroll
;   for (int d0 = 0; d0 < 12; ++d0) { int cb = (d0 * 16 + hi * 8) * 2;
;     bf16x8 b0 = *reinterpret_cast<const bf16x8*>(Ks + KSWZ(r32, cb));
;     bf16x8 b1 = *reinterpret_cast<const bf16x8*>(Ks + KSWZ(32 + r32, cb));
;     p0 = __builtin_amdgcn_mfma_f32_32x32x16_bf16(b0, qr[d0], p0, 0, 0, 0);
;     p1 = __builtin_amdgcn_mfma_f32_32x32x16_bf16(b1, qr[d0], p1, 0, 0, 0); }
; }
; __device__ __forceinline__ void attn_body(const u16* __restrict__ Qb, const u16* __restrict__ Kh, const u16* __restrict__ Vh,
;                                           u16* __restrict__ Ob, int seq, int wvs) {
;     ...
;     TBAR(5);
;     ISSUE_K(j + 2, NEXT3(NEXT3(sK))); ISSUE_V(j + 1, NEXT3(NEXT3(sV)));
;     qkt(pB0, pB1, K_lds + sK * SHM_K, qr, r32, hi);
;     finishSM(pA0, pA1, alA, l_reg, pa0, pa1, pa2, pa3);
.LBB0_331:
	s_waitcnt vmcnt(5) lgkmcnt(0)
	s_barrier
	s_add_i32 s4, s31, 1
	s_cmp_lg_u32 s31, 2
	s_cselect_b32 s13, s4, 0
	s_mul_i32 s15, s13, 0x6000
	s_add_i32 s10, s15, 0x6000
	s_cmp_eq_u32 s13, 2
	s_cselect_b64 s[4:5], -1, 0
	s_and_b64 s[8:9], s[4:5], exec
	s_cselect_b32 s8, 0, s10
	s_lshl_b32 vcc_lo, s69, 4
	s_add_i32 vcc_lo, vcc_lo, s8
	s_add_i32 vcc_hi, vcc_lo, 0xc000
	s_mov_b32 m0, vcc_hi
	s_add_i32 vcc_hi, vcc_lo, 0xe000
	global_load_lds_dwordx4 v166, s[98:99]
	s_mov_b32 m0, vcc_hi
	s_add_i32 vcc_hi, vcc_lo, 0x10000
	global_load_lds_dwordx4 v167, s[98:99]
	s_mov_b32 m0, vcc_hi
	s_add_i32 s8, s12, 1
	s_cmp_lg_u32 s12, 2
	s_cselect_b32 s16, s8, 0
	s_lshl_b32 s14, s16, 14
	s_add_i32 s17, s14, 0x4000
	s_cmp_eq_u32 s16, 2
	s_cselect_b64 s[8:9], -1, 0
	s_and_b64 s[10:11], s[8:9], exec
	s_cselect_b32 s10, 0, s17
	global_load_lds_dwordx4 v168, s[98:99]
	s_lshl_b32 vcc_lo, s69, 4
	s_add_i32 vcc_lo, vcc_lo, s10
	s_mov_b32 m0, vcc_lo
	s_add_i32 vcc_hi, vcc_lo, 0x2000
	global_load_lds_dwordx4 v169, s[100:101]
	s_mov_b32 m0, vcc_hi
	s_add_u32 s98, s98, 0x6000
	s_addc_u32 s99, s99, 0
	global_load_lds_dwordx4 v170, s[100:101]
	s_add_u32 s100, s100, 0x4000
	s_addc_u32 s101, s101, 0
	s_mul_i32 s10, s31, 0x6000
	s_add_i32 s10, s10, 0
	v_add_u32_e32 v162, s10, v193
	v_add_u32_e32 v253, s10, v199
	v_add_u32_e32 v252, s10, v200
	v_add_u32_e32 v244, s10, v202
	ds_read_b128 v[64:67], v162 offset:49152
	ds_read_b128 v[68:71], v162 offset:61440
	ds_read_b128 v[228:231], v253 offset:49152
	ds_read_b128 v[232:235], v253 offset:61440
	s_waitcnt lgkmcnt(2)
	v_mfma_f32_32x32x16_bf16 v[80:95], v[64:67], v[140:143], 0
	ds_read_b128 v[236:239], v252 offset:49152
	ds_read_b128 v[240:243], v252 offset:61440
	v_exp_f32_e32 v158, v158
	v_exp_f32_e32 v159, v159
	v_exp_f32_e32 v156, v156
	v_exp_f32_e32 v157, v157
	v_mfma_f32_32x32x16_bf16 v[64:79], v[68:71], v[140:143], 0
	v_exp_f32_e32 v154, v154
	v_exp_f32_e32 v155, v155
	v_exp_f32_e32 v163, v153
	v_exp_f32_e32 v206, v150
	v_exp_f32_e32 v227, v151
	v_cvt_pk_bf16_f32 v150, v214, v216
	v_cvt_pk_bf16_f32 v151, v217, v219
	s_waitcnt lgkmcnt(2)
	v_mfma_f32_32x32x16_bf16 v[64:79], v[232:235], v[136:139], v[64:79]
	v_cvt_pk_bf16_f32 v153, v156, v157
	v_mfma_f32_32x32x16_bf16 v[80:95], v[228:231], v[136:139], v[80:95]
	ds_read_b128 v[228:231], v244 offset:49152
	ds_read_b128 v[232:235], v244 offset:61440
	s_waitcnt lgkmcnt(2)
	v_mfma_f32_32x32x16_bf16 v[64:79], v[240:243], v[132:135], v[64:79]
	v_mfma_f32_32x32x16_bf16 v[80:95], v[236:239], v[132:135], v[80:95]
	ds_read_b128 v[236:239], v162 offset:49280
	ds_read_b128 v[240:243], v162 offset:61568
	s_waitcnt lgkmcnt(2)
	v_mfma_f32_32x32x16_bf16 v[64:79], v[232:235], v[128:131], v[64:79]
	v_mfma_f32_32x32x16_bf16 v[80:95], v[228:231], v[128:131], v[80:95]
	ds_read_b128 v[228:231], v253 offset:49280
	ds_read_b128 v[232:235], v253 offset:61568
	s_waitcnt lgkmcnt(2)
	v_mfma_f32_32x32x16_bf16 v[64:79], v[240:243], v[124:127], v[64:79]
	v_mfma_f32_32x32x16_bf16 v[80:95], v[236:239], v[124:127], v[80:95]
	ds_read_b128 v[236:239], v252 offset:49280
	ds_read_b128 v[240:243], v252 offset:61568
	s_waitcnt lgkmcnt(2)
	v_mfma_f32_32x32x16_bf16 v[64:79], v[232:235], v[120:123], v[64:79]
	v_mfma_f32_32x32x16_bf16 v[80:95], v[228:231], v[120:123], v[80:95]
	ds_read_b128 v[228:231], v244 offset:49280
	ds_read_b128 v[232:235], v244 offset:61568
	s_waitcnt lgkmcnt(2)
	v_mfma_f32_32x32x16_bf16 v[64:79], v[240:243], v[116:119], v[64:79]
	v_mfma_f32_32x32x16_bf16 v[80:95], v[236:239], v[116:119], v[80:95]
	ds_read_b128 v[236:239], v162 offset:49408
	ds_read_b128 v[240:243], v162 offset:61696
	s_waitcnt lgkmcnt(2)
	v_mfma_f32_32x32x16_bf16 v[64:79], v[232:235], v[112:115], v[64:79]
	v_mfma_f32_32x32x16_bf16 v[80:95], v[228:231], v[112:115], v[80:95]
	ds_read_b128 v[228:231], v253 offset:49408
	ds_read_b128 v[232:235], v253 offset:61696
	s_waitcnt lgkmcnt(2)
	v_mfma_f32_32x32x16_bf16 v[64:79], v[240:243], v[108:111], v[64:79]
	v_mfma_f32_32x32x16_bf16 v[80:95], v[236:239], v[108:111], v[80:95]
	ds_read_b128 v[236:239], v252 offset:49408
	ds_read_b128 v[240:243], v252 offset:61696
	s_waitcnt lgkmcnt(2)
	v_mfma_f32_32x32x16_bf16 v[64:79], v[232:235], v[104:107], v[64:79]
	v_mfma_f32_32x32x16_bf16 v[80:95], v[228:231], v[104:107], v[80:95]
	ds_read_b128 v[228:231], v244 offset:49408
	ds_read_b128 v[232:235], v244 offset:61696
	v_lshl_add_u32 v252, s12, 14, v190
	ds_read_b64_tr_b16 v[244:245], v252
	ds_read_b64_tr_b16 v[246:247], v252 offset:2048
	ds_read_b64_tr_b16 v[248:249], v252 offset:4096
	ds_read_b64_tr_b16 v[250:251], v252 offset:6144
	v_exp_f32_e32 v162, v152
	v_cvt_pk_bf16_f32 v152, v158, v159
	s_waitcnt lgkmcnt(6)
	v_mfma_f32_32x32x16_bf16 v[64:79], v[240:243], v[100:103], v[64:79]
	v_mfma_f32_32x32x16_bf16 v[80:95], v[236:239], v[100:103], v[80:95]
	s_waitcnt lgkmcnt(4)
; __device__ __forceinline__ void partialSM(f32x16& p0, f32x16& p1, float& m_reg, float& mn, float& alpha) {
;   constexpr float C = ASCALE * 1.4426950408889634f;
;   float pmax = p0[0]; for (int r = 1; r < 16; ++r) pmax = fmaxf(pmax, p0[r]); for (int r = 0; r < 16; ++r) pmax = fmaxf(pmax, p1[r]);
;   { auto rr = __builtin_amdgcn_permlane32_swap(__float_as_uint(pmax), __float_as_uint(pmax), false, false);
;     pmax = fmaxf(__uint_as_float(rr[0]), __uint_as_float(rr[1])); }
;   if (__builtin_expect(__all(pmax - m_reg <= THR / ASCALE), 1)) { mn = m_reg; alpha = 1.f; }
;   else { mn = fmaxf(m_reg, pmax); alpha = __builtin_amdgcn_exp2f((m_reg - mn) * C); m_reg = mn; }
;   float mnC = -mn * C;
;   for (int r = 0; r < 16; ++r) p0[r] = fmaf(p0[r], C, mnC); for (int r = 0; r < 16; ++r) p1[r] = fmaf(p1[r], C, mnC);
;   for (int r = 0; r < 16; ++r) p0[r] = __builtin_amdgcn_exp2f(p0[r]);
; }
; __device__ __forceinline__ void finishSM(f32x16& p0, f32x16& p1, float alpha, float& l_reg, bf16x8& pa0, bf16x8& pa1, bf16x8& pa2, bf16x8& pa3) {
;   for (int r = 0; r < 16; ++r) p1[r] = __builtin_amdgcn_exp2f(p1[r]);
;   float ps = 0; for (int r = 0; r < 16; ++r) ps += p0[r]; for (int r = 0; r < 16; ++r) ps += p1[r];
;   { auto rr = __builtin_amdgcn_permlane32_swap(__float_as_uint(ps), __float_as_uint(ps), false, false);
;     ps = __uint_as_float(rr[0]) + __uint_as_float(rr[1]); }
;   l_reg = l_reg * alpha + ps;
;     ...
;   PK4(p0, 0, pa0); PK4(p0, 8, pa1); PK4(p1, 0, pa2); PK4(p1, 8, pa3);
;     ...
; }
; __device__ __forceinline__ void qkt(f32x16& p0, f32x16& p1, const char* Ks, const bf16x8* qr, int r32, int hi) {
;   p0 = f32x16{}; p1 = f32x16{};
; #pragma unroll
;   for (int d0 = 0; d0 < 12; ++d0) { int cb = (d0 * 16 + hi * 8) * 2;
;     bf16x8 b0 = *reinterpret_cast<const bf16x8*>(Ks + KSWZ(r32, cb));
;     bf16x8 b1 = *reinterpret_cast<const bf16x8*>(Ks + KSWZ(32 + r32, cb));
;     p0 = __builtin_amdgcn_mfma_f32_32x32x16_bf16(b0, qr[d0], p0, 0, 0, 0);
;     p1 = __builtin_amdgcn_mfma_f32_32x32x16_bf16(b1, qr[d0], p1, 0, 0, 0); }
; }
; __device__ __forceinline__ int v_st(int k, int c) { const int kk = (k & ~0xC) | ((k & 4) << 1) | ((k & 8) >> 1); return ((kk >> 3) * 4 + (c >> 5)) * 512 + ((kk & 7) * 32 + (c & 31)) * 2; }
; __device__ __forceinline__ int v_rd_base(int lane) { return ((lane & 3) << 3) | (((lane >> 2) & 3) << 6) | (((lane >> 4) & 1) << 5) | (((lane >> 5) & 1) << 8); }
	v_mfma_f32_32x32x16_bf16 v[64:79], v[232:235], v[96:99], v[64:79]
	v_exp_f32_e32 v232, v144
	v_add_f32_e32 v144, 0, v218
	v_add_f32_e32 v144, v220, v144
	v_add_f32_e32 v144, v221, v144
	v_add_f32_e32 v144, v222, v144
	v_add_f32_e32 v144, v223, v144
	v_add_f32_e32 v144, v225, v144
	v_add_f32_e32 v144, v224, v144
	v_add_f32_e32 v144, v226, v144
	v_add_f32_e32 v144, v211, v144
	v_add_f32_e32 v144, v212, v144
	v_add_f32_e32 v144, v213, v144
	v_add_f32_e32 v144, v215, v144
	v_add_f32_e32 v144, v214, v144
	v_add_f32_e32 v144, v216, v144
	v_add_f32_e32 v144, v217, v144
	v_add_f32_e32 v144, v219, v144
	v_add_f32_e32 v144, v158, v144
	v_add_f32_e32 v144, v159, v144
	v_add_f32_e32 v144, v156, v144
	v_add_f32_e32 v144, v157, v144
	v_add_f32_e32 v144, v154, v144
	v_add_f32_e32 v144, v155, v144
	v_mfma_f32_32x32x16_bf16 v[80:95], v[228:231], v[96:99], v[80:95]
	v_exp_f32_e32 v228, v148
	v_add_f32_e32 v144, v162, v144
	v_exp_f32_e32 v229, v149
	v_add_f32_e32 v144, v163, v144
	v_exp_f32_e32 v230, v146
	v_add_f32_e32 v144, v206, v144
	v_exp_f32_e32 v231, v147
	v_add_f32_e32 v144, v227, v144
	v_add_f32_e32 v144, v228, v144
	v_exp_f32_e32 v233, v145
	v_add_f32_e32 v144, v229, v144
	v_add_f32_e32 v144, v230, v144
	v_add_f32_e32 v144, v231, v144
	v_add_f32_e32 v144, v232, v144
	v_add_f32_e32 v209, v233, v144
	v_cvt_pk_bf16_f32 v144, v218, v220
	v_cvt_pk_bf16_f32 v145, v221, v222
	v_cvt_pk_bf16_f32 v146, v223, v225
	v_cvt_pk_bf16_f32 v147, v224, v226
	s_nop 0
	v_cvt_pk_bf16_f32 v154, v154, v155
	v_cvt_pk_bf16_f32 v155, v162, v163
	v_cvt_pk_bf16_f32 v148, v211, v212
	v_cvt_pk_bf16_f32 v149, v213, v215
	v_cvt_pk_bf16_f32 v156, v206, v227
	ds_read_b64_tr_b16 v[220:221], v252 offset:8192
	ds_read_b64_tr_b16 v[222:223], v252 offset:10240
	ds_read_b64_tr_b16 v[224:225], v252 offset:12288
	ds_read_b64_tr_b16 v[226:227], v252 offset:14336
	s_waitcnt lgkmcnt(4)
	v_mfma_f32_32x32x16_bf16 v[0:15], v[144:147], v[244:247], v[0:15]
	ds_read_b64_tr_b16 v[212:213], v252 offset:512
	ds_read_b64_tr_b16 v[214:215], v252 offset:2560
	v_mfma_f32_32x32x16_bf16 v[0:15], v[148:151], v[248:251], v[0:15]
	ds_read_b64_tr_b16 v[216:217], v252 offset:4608
	ds_read_b64_tr_b16 v[218:219], v252 offset:6656
	v_cvt_pk_bf16_f32 v157, v228, v229
	v_cvt_pk_bf16_f32 v158, v230, v231
	v_cvt_pk_bf16_f32 v159, v232, v233
	s_nop 0
	s_waitcnt lgkmcnt(6)
	v_mfma_f32_32x32x16_bf16 v[0:15], v[152:155], v[220:223], v[0:15]
	ds_read_b64_tr_b16 v[220:221], v252 offset:8704
	ds_read_b64_tr_b16 v[222:223], v252 offset:10752
	v_mov_b32_e32 v210, v209
	s_nop 1
	v_permlane32_swap_b32_e32 v209, v210
	v_mov_b32_e32 v211, 1.0
	s_waitcnt lgkmcnt(6)
	v_mfma_f32_32x32x16_bf16 v[0:15], v[156:159], v[224:227], v[0:15]
	ds_read_b64_tr_b16 v[224:225], v252 offset:12800
	ds_read_b64_tr_b16 v[226:227], v252 offset:14848
	s_waitcnt lgkmcnt(6)
	v_mfma_f32_32x32x16_bf16 v[48:63], v[144:147], v[212:215], v[48:63]
	ds_read_b64_tr_b16 v[212:213], v252 offset:1024
	ds_read_b64_tr_b16 v[214:215], v252 offset:3072
	s_waitcnt lgkmcnt(6)
	v_mfma_f32_32x32x16_bf16 v[48:63], v[148:151], v[216:219], v[48:63]
	ds_read_b64_tr_b16 v[216:217], v252 offset:5120
	ds_read_b64_tr_b16 v[218:219], v252 offset:7168
	s_waitcnt lgkmcnt(6)
	v_mfma_f32_32x32x16_bf16 v[48:63], v[152:155], v[220:223], v[48:63]
	ds_read_b64_tr_b16 v[220:221], v252 offset:9216
	ds_read_b64_tr_b16 v[222:223], v252 offset:11264
	s_waitcnt lgkmcnt(6)
	v_mfma_f32_32x32x16_bf16 v[48:63], v[156:159], v[224:227], v[48:63]
	ds_read_b64_tr_b16 v[224:225], v252 offset:13312
	ds_read_b64_tr_b16 v[226:227], v252 offset:15360
	s_waitcnt lgkmcnt(6)
	v_mfma_f32_32x32x16_bf16 v[32:47], v[144:147], v[212:215], v[32:47]
	ds_read_b64_tr_b16 v[212:213], v252 offset:1536
	ds_read_b64_tr_b16 v[214:215], v252 offset:3584
	s_waitcnt lgkmcnt(6)
	v_mfma_f32_32x32x16_bf16 v[32:47], v[148:151], v[216:219], v[32:47]
	ds_read_b64_tr_b16 v[216:217], v252 offset:5632
	ds_read_b64_tr_b16 v[218:219], v252 offset:7680
	s_waitcnt lgkmcnt(6)
	v_mfma_f32_32x32x16_bf16 v[32:47], v[152:155], v[220:223], v[32:47]
	ds_read_b64_tr_b16 v[220:221], v252 offset:9728
	ds_read_b64_tr_b16 v[222:223], v252 offset:11776
	s_waitcnt lgkmcnt(6)
	v_mfma_f32_32x32x16_bf16 v[32:47], v[156:159], v[224:227], v[32:47]
	ds_read_b64_tr_b16 v[224:225], v252 offset:13824
	ds_read_b64_tr_b16 v[226:227], v252 offset:15872
	s_waitcnt lgkmcnt(6)
	v_mfma_f32_32x32x16_bf16 v[16:31], v[144:147], v[212:215], v[16:31]
	v_max_f32_e32 v144, v80, v81
	v_max3_f32 v144, v144, v82, v83
	v_max3_f32 v144, v144, v84, v85
	v_max3_f32 v144, v144, v86, v87
	v_max3_f32 v144, v144, v88, v89
	s_waitcnt lgkmcnt(4)
	v_mfma_f32_32x32x16_bf16 v[16:31], v[148:151], v[216:219], v[16:31]
	v_max3_f32 v144, v144, v90, v91
	v_max3_f32 v144, v144, v92, v93
	v_max3_f32 v144, v144, v94, v95
	v_max3_f32 v144, v144, v64, v65
	v_max3_f32 v144, v144, v66, v67
	v_max3_f32 v144, v144, v68, v69
	v_max3_f32 v144, v144, v70, v71
	s_waitcnt lgkmcnt(2)
	v_mfma_f32_32x32x16_bf16 v[16:31], v[152:155], v[220:223], v[16:31]
	v_max3_f32 v144, v144, v72, v73
	v_max3_f32 v144, v144, v74, v75
	v_max3_f32 v144, v144, v76, v77
	v_max3_f32 v144, v144, v78, v79
	v_mov_b32_e32 v145, v144
	s_nop 1
	v_permlane32_swap_b32_e32 v144, v145
	s_waitcnt lgkmcnt(0)
	v_mfma_f32_32x32x16_bf16 v[16:31], v[156:159], v[224:227], v[16:31]
	v_max_f32_e32 v144, v144, v145
	v_sub_f32_e32 v145, v144, v191
	v_cmp_ge_f32_e32 vcc, s35, v145
	s_cmp_eq_u64 vcc, exec
	s_cbranch_scc0 .LBB0_344
	v_cmp_gt_f32_e32 vcc, 1.0, v211
	s_cbranch_vccz .LBB0_336

; #define ISSUE_K(t, slot) do { const char* kg_ = (const char*)(Kh + (long)(t) * (KVBLK * 192)); char* kl_ = K_lds + (slot) * SHM_K + tid * 16; \
;     DMA16(kg_ + kso0, kl_); DMA16(kg_ + kso1, kl_ + 8192); DMA16(kg_ + kso2, kl_ + 16384); } while (0)
; #define ISSUE_V(t, slot) do { const char* vg_ = (const char*)(Vh + (long)(t) * (KVBLK * 128)); char* vl_ = V_lds + (slot) * SHM_V + tid * 16; \
;     DMA16(vg_ + vso0, vl_); DMA16(vg_ + vso1, vl_ + 8192); } while (0)
; #define TBAR(n) do { asm volatile("s_waitcnt vmcnt(" #n ") lgkmcnt(0)" ::: "memory"); __builtin_amdgcn_s_barrier(); SBAR(); } while (0)
; __device__ __forceinline__ void partialSM(f32x16& p0, f32x16& p1, float& m_reg, float& mn, float& alpha) {
;     ...
;   else { mn = fmaxf(m_reg, pmax); alpha = __builtin_amdgcn_exp2f((m_reg - mn) * C); m_reg = mn; }
;   float mnC = -mn * C;
;   for (int r = 0; r < 16; ++r) p0[r] = fmaf(p0[r], C, mnC); for (int r = 0; r < 16; ++r) p1[r] = fmaf(p1[r], C, mnC);
;   for (int r = 0; r < 16; ++r) p0[r] = __builtin_amdgcn_exp2f(p0[r]);
; __device__ __forceinline__ void attn_body(const u16* __restrict__ Qb, const u16* __restrict__ Kh, const u16* __restrict__ Vh,
;                                           u16* __restrict__ Ob, int seq, int wvs) {
;     ...
;     TBAR(5);
;     if (j + 3 < NT) ISSUE_K(j + 3, NEXT3(NEXT3(sK)));
;     ISSUE_V(j + 2, NEXT3(NEXT3(sV)));
;     qkt(pA0, pA1, K_lds + sK * SHM_K, qr, r32, hi);
;     finishSM(pB0, pB1, alB, l_reg, pa0, pa1, pa2, pa3);
;     pv_d0(o, vb0 + sV * SHM_V, pa0, pa1, pa2, pa3); partialSM(pA0, pA1, m_reg, mnA, alA);
.LBB0_338:
	s_add_u32 s98, s98, 0x6000
	s_addc_u32 s99, s99, 0
	s_add_i32 s16, s16, 1
	s_and_b64 s[8:9], s[8:9], exec
	s_cselect_b32 s12, 0, s16
	s_lshl_b32 s17, s12, 14
	s_add_i32 s8, s17, 0x4000
	s_cmp_lg_u32 s12, 2
	v_mul_f32_e32 v180, 0xbdd53b94, v191
	s_cselect_b32 s16, s8, 0
	v_fmamk_f32 v221, v66, 0x3dd53b94, v180
	v_fmamk_f32 v219, v64, 0x3dd53b94, v180
	v_fmamk_f32 v220, v65, 0x3dd53b94, v180
	s_lshl_b32 vcc_lo, s69, 4
	s_add_i32 vcc_lo, vcc_lo, s16
	s_mov_b32 m0, vcc_lo
	s_add_i32 vcc_hi, vcc_lo, 0x2000
	global_load_lds_dwordx4 v169, s[100:101]
	s_mov_b32 m0, vcc_hi
	s_add_i32 s8, s15, 0
	v_fmamk_f32 v218, v68, 0x3dd53b94, v180
	global_load_lds_dwordx4 v170, s[100:101]
	s_add_u32 s100, s100, 0x4000
	s_addc_u32 s101, s101, 0
	v_add_u32_e32 v68, s8, v193
	v_fmamk_f32 v217, v67, 0x3dd53b94, v180
	v_fmamk_f32 v181, v69, 0x3dd53b94, v180
	v_fmamk_f32 v182, v70, 0x3dd53b94, v180
	v_fmamk_f32 v183, v71, 0x3dd53b94, v180
	ds_read_b128 v[64:67], v68 offset:49152
	ds_read_b128 v[68:71], v68 offset:61440
	v_add_u32_e32 v162, s8, v193
	v_add_u32_e32 v253, s8, v199
	v_add_u32_e32 v252, s8, v200
	v_add_u32_e32 v244, s8, v202
	ds_read_b128 v[176:179], v253 offset:49152
	ds_read_b128 v[222:225], v253 offset:61440
	v_fmamk_f32 v80, v80, 0x3dd53b94, v180
	v_fmamk_f32 v81, v81, 0x3dd53b94, v180
	v_fmamk_f32 v82, v82, 0x3dd53b94, v180
	v_fmamk_f32 v83, v83, 0x3dd53b94, v180
	v_fmamk_f32 v84, v84, 0x3dd53b94, v180
	v_fmamk_f32 v85, v85, 0x3dd53b94, v180
	v_fmamk_f32 v86, v86, 0x3dd53b94, v180
	v_fmamk_f32 v87, v87, 0x3dd53b94, v180
	v_fmamk_f32 v88, v88, 0x3dd53b94, v180
	v_fmamk_f32 v89, v89, 0x3dd53b94, v180
	v_fmamk_f32 v90, v90, 0x3dd53b94, v180
	v_fmamk_f32 v91, v91, 0x3dd53b94, v180
	v_fmamk_f32 v92, v92, 0x3dd53b94, v180
	v_fmamk_f32 v93, v93, 0x3dd53b94, v180
	v_fmamk_f32 v94, v94, 0x3dd53b94, v180
	v_fmamk_f32 v95, v95, 0x3dd53b94, v180
	v_exp_f32_e32 v144, v80
	v_exp_f32_e32 v145, v81
	v_exp_f32_e32 v146, v82
	v_exp_f32_e32 v156, v83
	v_exp_f32_e32 v147, v84
	v_exp_f32_e32 v157, v85
	v_exp_f32_e32 v158, v86
	v_exp_f32_e32 v159, v87
	v_exp_f32_e32 v148, v88
	v_exp_f32_e32 v150, v89
	v_exp_f32_e32 v149, v90
	v_exp_f32_e32 v151, v91
	v_exp_f32_e32 v152, v92
	v_exp_f32_e32 v153, v93
	v_exp_f32_e32 v154, v94
	v_exp_f32_e32 v155, v95
	s_waitcnt lgkmcnt(2)
	v_mfma_f32_32x32x16_bf16 v[80:95], v[64:67], v[140:143], 0
	ds_read_b128 v[236:239], v252 offset:49152
	ds_read_b128 v[240:243], v252 offset:61440
	v_fmamk_f32 v184, v72, 0x3dd53b94, v180
	v_fmamk_f32 v185, v73, 0x3dd53b94, v180
	v_fmamk_f32 v212, v74, 0x3dd53b94, v180
	v_fmamk_f32 v213, v75, 0x3dd53b94, v180
	v_fmamk_f32 v214, v76, 0x3dd53b94, v180
	v_fmamk_f32 v215, v77, 0x3dd53b94, v180
	v_fmamk_f32 v216, v78, 0x3dd53b94, v180
	v_fmac_f32_e32 v180, 0x3dd53b94, v79
	v_mfma_f32_32x32x16_bf16 v[64:79], v[68:71], v[140:143], 0
	v_exp_f32_e32 v163, v220
	v_exp_f32_e32 v206, v218
	v_exp_f32_e32 v181, v181
	v_exp_f32_e32 v182, v182
	v_exp_f32_e32 v183, v183
	s_waitcnt lgkmcnt(2)
	v_mfma_f32_32x32x16_bf16 v[80:95], v[176:179], v[136:139], v[80:95]
	v_exp_f32_e32 v184, v184
	v_exp_f32_e32 v185, v185
	v_exp_f32_e32 v212, v212
	v_exp_f32_e32 v213, v213
	v_exp_f32_e32 v214, v214
	v_exp_f32_e32 v215, v215
	v_exp_f32_e32 v216, v216
	v_mfma_f32_32x32x16_bf16 v[64:79], v[222:225], v[136:139], v[64:79]
	ds_read_b128 v[176:179], v244 offset:49152
	ds_read_b128 v[222:225], v244 offset:61440
	v_exp_f32_e32 v180, v180
	s_waitcnt lgkmcnt(2)
	v_mfma_f32_32x32x16_bf16 v[80:95], v[236:239], v[132:135], v[80:95]
	v_mfma_f32_32x32x16_bf16 v[64:79], v[240:243], v[132:135], v[64:79]
	ds_read_b128 v[236:239], v162 offset:49280
	ds_read_b128 v[240:243], v162 offset:61568
	s_waitcnt lgkmcnt(2)
	v_mfma_f32_32x32x16_bf16 v[80:95], v[176:179], v[128:131], v[80:95]
	v_mfma_f32_32x32x16_bf16 v[64:79], v[222:225], v[128:131], v[64:79]
	ds_read_b128 v[176:179], v253 offset:49280
	ds_read_b128 v[222:225], v253 offset:61568
	s_waitcnt lgkmcnt(2)
	v_mfma_f32_32x32x16_bf16 v[80:95], v[236:239], v[124:127], v[80:95]
	v_mfma_f32_32x32x16_bf16 v[64:79], v[240:243], v[124:127], v[64:79]
	ds_read_b128 v[236:239], v252 offset:49280
	ds_read_b128 v[240:243], v252 offset:61568
	s_waitcnt lgkmcnt(2)
	v_mfma_f32_32x32x16_bf16 v[80:95], v[176:179], v[120:123], v[80:95]
	v_mfma_f32_32x32x16_bf16 v[64:79], v[222:225], v[120:123], v[64:79]
	ds_read_b128 v[176:179], v244 offset:49280
	ds_read_b128 v[222:225], v244 offset:61568
	s_waitcnt lgkmcnt(2)
	v_mfma_f32_32x32x16_bf16 v[80:95], v[236:239], v[116:119], v[80:95]
	v_mfma_f32_32x32x16_bf16 v[64:79], v[240:243], v[116:119], v[64:79]
	ds_read_b128 v[236:239], v162 offset:49408
	ds_read_b128 v[240:243], v162 offset:61696
	s_waitcnt lgkmcnt(2)
	v_mfma_f32_32x32x16_bf16 v[80:95], v[176:179], v[112:115], v[80:95]
	v_mfma_f32_32x32x16_bf16 v[64:79], v[222:225], v[112:115], v[64:79]
	ds_read_b128 v[176:179], v253 offset:49408
	ds_read_b128 v[222:225], v253 offset:61696
	s_waitcnt lgkmcnt(2)
	v_mfma_f32_32x32x16_bf16 v[80:95], v[236:239], v[108:111], v[80:95]
	v_mfma_f32_32x32x16_bf16 v[64:79], v[240:243], v[108:111], v[64:79]
	ds_read_b128 v[236:239], v252 offset:49408
	ds_read_b128 v[240:243], v252 offset:61696
	s_waitcnt lgkmcnt(2)
	v_mfma_f32_32x32x16_bf16 v[80:95], v[176:179], v[104:107], v[80:95]
	v_mfma_f32_32x32x16_bf16 v[64:79], v[222:225], v[104:107], v[64:79]
	ds_read_b128 v[176:179], v244 offset:49408
	ds_read_b128 v[222:225], v244 offset:61696
	v_add_u32_e32 v252, s14, v190
	ds_read_b64_tr_b16 v[244:245], v252
	ds_read_b64_tr_b16 v[246:247], v252 offset:2048
	ds_read_b64_tr_b16 v[248:249], v252 offset:4096
	ds_read_b64_tr_b16 v[250:251], v252 offset:6144
	v_exp_f32_e32 v162, v219
	s_waitcnt lgkmcnt(6)
; __device__ __forceinline__ void partialSM(f32x16& p0, f32x16& p1, float& m_reg, float& mn, float& alpha) {
;   constexpr float C = ASCALE * 1.4426950408889634f;
;   float pmax = p0[0]; for (int r = 1; r < 16; ++r) pmax = fmaxf(pmax, p0[r]); for (int r = 0; r < 16; ++r) pmax = fmaxf(pmax, p1[r]);
;   { auto rr = __builtin_amdgcn_permlane32_swap(__float_as_uint(pmax), __float_as_uint(pmax), false, false);
;     pmax = fmaxf(__uint_as_float(rr[0]), __uint_as_float(rr[1])); }
;   if (__builtin_expect(__all(pmax - m_reg <= THR / ASCALE), 1)) { mn = m_reg; alpha = 1.f; }
;   else { mn = fmaxf(m_reg, pmax); alpha = __builtin_amdgcn_exp2f((m_reg - mn) * C); m_reg = mn; }
;   float mnC = -mn * C;
;   for (int r = 0; r < 16; ++r) p0[r] = fmaf(p0[r], C, mnC); for (int r = 0; r < 16; ++r) p1[r] = fmaf(p1[r], C, mnC);
;   for (int r = 0; r < 16; ++r) p0[r] = __builtin_amdgcn_exp2f(p0[r]);
; }
; __device__ __forceinline__ void finishSM(f32x16& p0, f32x16& p1, float alpha, float& l_reg, bf16x8& pa0, bf16x8& pa1, bf16x8& pa2, bf16x8& pa3) {
;   for (int r = 0; r < 16; ++r) p1[r] = __builtin_amdgcn_exp2f(p1[r]);
;   float ps = 0; for (int r = 0; r < 16; ++r) ps += p0[r]; for (int r = 0; r < 16; ++r) ps += p1[r];
;   { auto rr = __builtin_amdgcn_permlane32_swap(__float_as_uint(ps), __float_as_uint(ps), false, false);
;     ps = __uint_as_float(rr[0]) + __uint_as_float(rr[1]); }
;   l_reg = l_reg * alpha + ps;
;     ...
;   PK4(p0, 0, pa0); PK4(p0, 8, pa1); PK4(p1, 0, pa2); PK4(p1, 8, pa3);
;     ...
; }
; __device__ __forceinline__ void qkt(f32x16& p0, f32x16& p1, const char* Ks, const bf16x8* qr, int r32, int hi) {
;   p0 = f32x16{}; p1 = f32x16{};
; #pragma unroll
;   for (int d0 = 0; d0 < 12; ++d0) { int cb = (d0 * 16 + hi * 8) * 2;
;     bf16x8 b0 = *reinterpret_cast<const bf16x8*>(Ks + KSWZ(r32, cb));
;     bf16x8 b1 = *reinterpret_cast<const bf16x8*>(Ks + KSWZ(32 + r32, cb));
;     p0 = __builtin_amdgcn_mfma_f32_32x32x16_bf16(b0, qr[d0], p0, 0, 0, 0);
;     p1 = __builtin_amdgcn_mfma_f32_32x32x16_bf16(b1, qr[d0], p1, 0, 0, 0); }
; }
; __device__ __forceinline__ int v_st(int k, int c) { const int kk = (k & ~0xC) | ((k & 4) << 1) | ((k & 8) >> 1); return ((kk >> 3) * 4 + (c >> 5)) * 512 + ((kk & 7) * 32 + (c & 31)) * 2; }
; __device__ __forceinline__ int v_rd_base(int lane) { return ((lane & 3) << 3) | (((lane >> 2) & 3) << 6) | (((lane >> 4) & 1) << 5) | (((lane >> 5) & 1) << 8); }
	v_mfma_f32_32x32x16_bf16 v[80:95], v[236:239], v[100:103], v[80:95]
	v_mfma_f32_32x32x16_bf16 v[64:79], v[240:243], v[100:103], v[64:79]
	s_waitcnt lgkmcnt(4)
	v_mfma_f32_32x32x16_bf16 v[80:95], v[176:179], v[96:99], v[80:95]
	v_add_f32_e32 v177, 0, v144
	v_add_f32_e32 v177, v145, v177
	v_add_f32_e32 v177, v146, v177
	v_add_f32_e32 v177, v156, v177
	v_add_f32_e32 v177, v147, v177
	v_add_f32_e32 v177, v157, v177
	v_add_f32_e32 v177, v158, v177
	v_add_f32_e32 v177, v159, v177
	v_add_f32_e32 v177, v148, v177
	v_add_f32_e32 v177, v150, v177
	v_add_f32_e32 v177, v149, v177
	v_add_f32_e32 v177, v151, v177
	v_add_f32_e32 v177, v152, v177
	v_add_f32_e32 v177, v153, v177
	v_exp_f32_e32 v176, v221
	v_add_f32_e32 v177, v154, v177
	v_exp_f32_e32 v179, v217
	v_add_f32_e32 v177, v155, v177
	v_add_f32_e32 v177, v162, v177
	v_add_f32_e32 v177, v163, v177
	v_add_f32_e32 v177, v176, v177
	v_add_f32_e32 v177, v179, v177
	v_add_f32_e32 v177, v206, v177
	v_add_f32_e32 v177, v181, v177
	v_add_f32_e32 v177, v182, v177
	v_add_f32_e32 v177, v183, v177
	v_add_f32_e32 v177, v184, v177
	v_add_f32_e32 v177, v185, v177
	v_cvt_pk_bf16_f32 v144, v144, v145
	v_cvt_pk_bf16_f32 v145, v146, v156
	v_cvt_pk_bf16_f32 v146, v147, v157
	v_cvt_pk_bf16_f32 v147, v158, v159
	v_add_f32_e32 v177, v212, v177
	v_add_f32_e32 v177, v213, v177
	v_add_f32_e32 v177, v214, v177
	v_add_f32_e32 v177, v215, v177
	v_add_f32_e32 v177, v216, v177
	v_cvt_pk_bf16_f32 v148, v148, v150
	v_cvt_pk_bf16_f32 v150, v152, v153
	v_cvt_pk_bf16_f32 v152, v162, v163
	v_mfma_f32_32x32x16_bf16 v[64:79], v[222:225], v[96:99], v[64:79]
	v_add_f32_e32 v177, v180, v177
	v_cvt_pk_bf16_f32 v149, v149, v151
	v_cvt_pk_bf16_f32 v151, v154, v155
	v_cvt_pk_bf16_f32 v154, v206, v181
	v_cvt_pk_bf16_f32 v155, v182, v183
	v_cvt_pk_bf16_f32 v157, v212, v213
	v_cvt_pk_bf16_f32 v158, v214, v215
	v_cvt_pk_bf16_f32 v159, v216, v180
	ds_read_b64_tr_b16 v[216:217], v252 offset:8192
	ds_read_b64_tr_b16 v[218:219], v252 offset:10240
	ds_read_b64_tr_b16 v[220:221], v252 offset:12288
	ds_read_b64_tr_b16 v[222:223], v252 offset:14336
	s_waitcnt lgkmcnt(4)
	v_mfma_f32_32x32x16_bf16 v[0:15], v[144:147], v[244:247], v[0:15]
	ds_read_b64_tr_b16 v[180:181], v252 offset:512
	ds_read_b64_tr_b16 v[182:183], v252 offset:2560
	v_cvt_pk_bf16_f32 v153, v176, v179
	v_mfma_f32_32x32x16_bf16 v[0:15], v[148:151], v[248:251], v[0:15]
	ds_read_b64_tr_b16 v[212:213], v252 offset:4608
	ds_read_b64_tr_b16 v[214:215], v252 offset:6656
	v_cvt_pk_bf16_f32 v156, v184, v185
	s_nop 1
	s_waitcnt lgkmcnt(6)
	v_mfma_f32_32x32x16_bf16 v[0:15], v[152:155], v[216:219], v[0:15]
	ds_read_b64_tr_b16 v[216:217], v252 offset:8704
	ds_read_b64_tr_b16 v[218:219], v252 offset:10752
	v_mov_b32_e32 v178, v177
	s_nop 1
	v_permlane32_swap_b32_e32 v177, v178
	s_waitcnt lgkmcnt(6)
	v_mfma_f32_32x32x16_bf16 v[0:15], v[156:159], v[220:223], v[0:15]
	ds_read_b64_tr_b16 v[220:221], v252 offset:12800
	ds_read_b64_tr_b16 v[222:223], v252 offset:14848
	s_waitcnt lgkmcnt(6)
	v_mfma_f32_32x32x16_bf16 v[48:63], v[144:147], v[180:183], v[48:63]
	ds_read_b64_tr_b16 v[180:181], v252 offset:1024
	ds_read_b64_tr_b16 v[182:183], v252 offset:3072
	s_waitcnt lgkmcnt(6)
	v_mfma_f32_32x32x16_bf16 v[48:63], v[148:151], v[212:215], v[48:63]
	ds_read_b64_tr_b16 v[212:213], v252 offset:5120
	ds_read_b64_tr_b16 v[214:215], v252 offset:7168
	s_waitcnt lgkmcnt(6)
	v_mfma_f32_32x32x16_bf16 v[48:63], v[152:155], v[216:219], v[48:63]
	ds_read_b64_tr_b16 v[216:217], v252 offset:9216
	ds_read_b64_tr_b16 v[218:219], v252 offset:11264
	s_waitcnt lgkmcnt(6)
	v_mfma_f32_32x32x16_bf16 v[48:63], v[156:159], v[220:223], v[48:63]
	ds_read_b64_tr_b16 v[220:221], v252 offset:13312
	ds_read_b64_tr_b16 v[222:223], v252 offset:15360
	s_waitcnt lgkmcnt(6)
	v_mfma_f32_32x32x16_bf16 v[32:47], v[144:147], v[180:183], v[32:47]
	ds_read_b64_tr_b16 v[180:181], v252 offset:1536
	ds_read_b64_tr_b16 v[182:183], v252 offset:3584
	s_waitcnt lgkmcnt(6)
	v_mfma_f32_32x32x16_bf16 v[32:47], v[148:151], v[212:215], v[32:47]
	ds_read_b64_tr_b16 v[212:213], v252 offset:5632
	ds_read_b64_tr_b16 v[214:215], v252 offset:7680
	s_waitcnt lgkmcnt(6)
	v_mfma_f32_32x32x16_bf16 v[32:47], v[152:155], v[216:219], v[32:47]
	ds_read_b64_tr_b16 v[216:217], v252 offset:9728
	ds_read_b64_tr_b16 v[218:219], v252 offset:11776
	s_waitcnt lgkmcnt(6)
	v_mfma_f32_32x32x16_bf16 v[32:47], v[156:159], v[220:223], v[32:47]
	ds_read_b64_tr_b16 v[220:221], v252 offset:13824
	ds_read_b64_tr_b16 v[222:223], v252 offset:15872
	s_waitcnt lgkmcnt(6)
	v_mfma_f32_32x32x16_bf16 v[16:31], v[144:147], v[180:183], v[16:31]
	v_max_f32_e32 v144, v80, v81
	v_max3_f32 v144, v144, v82, v83
	v_max3_f32 v144, v144, v84, v85
	v_max3_f32 v144, v144, v86, v87
	v_max3_f32 v144, v144, v88, v89
	v_max3_f32 v144, v144, v90, v91
	v_max3_f32 v144, v144, v92, v93
	s_waitcnt lgkmcnt(4)
	v_mfma_f32_32x32x16_bf16 v[16:31], v[148:151], v[212:215], v[16:31]
	v_max3_f32 v144, v144, v94, v95
	v_max3_f32 v144, v144, v64, v65
	v_max3_f32 v144, v144, v66, v67
	v_max3_f32 v144, v144, v68, v69
	v_max3_f32 v144, v144, v70, v71
	v_max3_f32 v144, v144, v72, v73
	v_max3_f32 v144, v144, v74, v75
	v_max3_f32 v144, v144, v76, v77
	s_waitcnt lgkmcnt(2)
	v_mfma_f32_32x32x16_bf16 v[16:31], v[152:155], v[216:219], v[16:31]
	v_max3_f32 v144, v144, v78, v79
	v_mov_b32_e32 v145, v144
	s_nop 1
	v_permlane32_swap_b32_e32 v144, v145
	v_max_f32_e32 v144, v144, v145
	v_sub_f32_e32 v145, v144, v191
	v_cmp_ge_f32_e32 vcc, s35, v145
	v_max_f32_e32 v144, v191, v144
	s_waitcnt lgkmcnt(0)
	v_mfma_f32_32x32x16_bf16 v[16:31], v[156:159], v[220:223], v[16:31]
	v_sub_f32_e32 v145, v191, v144
	v_mul_f32_e32 v145, 0x3dd53b94, v145
	v_exp_f32_e32 v145, v145
	s_cmp_eq_u64 vcc, exec
	s_cselect_b64 s[8:9], -1, 0
	v_cndmask_b32_e64 v176, v145, 1.0, s[8:9]
	v_cmp_gt_f32_e32 vcc, 1.0, v176
	s_cbranch_vccz .LBB0_342
	s_and_saveexec_b64 s[14:15], s[6:7]
	ds_write_b32 v188, v176 offset:128
	s_or_b64 exec, exec, s[14:15]
	s_waitcnt lgkmcnt(0)
	v_add_u32_e32 v145, v165, v160
	ds_read_b128 v[146:149], v145 offset:224
	ds_read_b128 v[150:153], v145 offset:192
	ds_read_b128 v[154:157], v145 offset:160
	ds_read_b128 v[180:183], v145 offset:128
	s_waitcnt lgkmcnt(0)
	v_pk_mul_f32 v[12:13], v[12:13], v[146:147]
	v_pk_mul_f32 v[8:9], v[8:9], v[150:151]
	v_pk_mul_f32 v[4:5], v[4:5], v[154:155]
	v_pk_mul_f32 v[14:15], v[14:15], v[148:149]
	v_pk_mul_f32 v[10:11], v[10:11], v[152:153]
	v_pk_mul_f32 v[6:7], v[6:7], v[156:157]
	v_pk_mul_f32 v[2:3], v[2:3], v[182:183]
	v_pk_mul_f32 v[0:1], v[0:1], v[180:181]
	v_pk_mul_f32 v[60:61], v[60:61], v[146:147]
	v_pk_mul_f32 v[56:57], v[56:57], v[150:151]
	v_pk_mul_f32 v[52:53], v[52:53], v[154:155]
	v_pk_mul_f32 v[62:63], v[62:63], v[148:149]
	v_pk_mul_f32 v[58:59], v[58:59], v[152:153]
	v_pk_mul_f32 v[54:55], v[54:55], v[156:157]
	v_pk_mul_f32 v[50:51], v[50:51], v[182:183]
	v_pk_mul_f32 v[48:49], v[48:49], v[180:181]
	v_pk_mul_f32 v[44:45], v[44:45], v[146:147]
	v_pk_mul_f32 v[40:41], v[40:41], v[150:151]
	v_pk_mul_f32 v[36:37], v[36:37], v[154:155]
	v_pk_mul_f32 v[46:47], v[46:47], v[148:149]
	v_pk_mul_f32 v[42:43], v[42:43], v[152:153]
	v_pk_mul_f32 v[38:39], v[38:39], v[156:157]
	v_pk_mul_f32 v[34:35], v[34:35], v[182:183]
	v_pk_mul_f32 v[32:33], v[32:33], v[180:181]
	v_pk_mul_f32 v[28:29], v[28:29], v[146:147]
	v_pk_mul_f32 v[24:25], v[24:25], v[150:151]
	v_pk_mul_f32 v[20:21], v[20:21], v[154:155]
	v_pk_mul_f32 v[30:31], v[30:31], v[148:149]
	v_pk_mul_f32 v[26:27], v[26:27], v[152:153]
	v_pk_mul_f32 v[22:23], v[22:23], v[156:157]
	v_pk_mul_f32 v[18:19], v[18:19], v[182:183]
	v_pk_mul_f32 v[16:17], v[16:17], v[180:181]

; __device__ __forceinline__ void partialSM(f32x16& p0, f32x16& p1, float& m_reg, float& mn, float& alpha) {
;     ...
;   if (__builtin_expect(__all(pmax - m_reg <= THR / ASCALE), 1)) { mn = m_reg; alpha = 1.f; }
;   else { mn = fmaxf(m_reg, pmax); alpha = __builtin_amdgcn_exp2f((m_reg - mn) * C); m_reg = mn; }
.LBB0_344:
	v_max_f32_e32 v144, v144, v144
	v_max_f32_e32 v144, v191, v144
	v_sub_f32_e32 v145, v191, v144
	v_mul_f32_e32 v145, 0x3dd53b94, v145
	v_exp_f32_e32 v211, v145
	v_mov_b32_e32 v191, v144
	v_cmp_gt_f32_e32 vcc, 1.0, v211
	s_cbranch_vccnz .LBB0_333
	s_branch .LBB0_336

; #define SBAR() __builtin_amdgcn_sched_barrier(0)
; #define TBAR(n) do { asm volatile("s_waitcnt vmcnt(" #n ") lgkmcnt(0)" ::: "memory"); __builtin_amdgcn_s_barrier(); SBAR(); } while (0)
; __device__ __forceinline__ void finishSM(f32x16& p0, f32x16& p1, float alpha, float& l_reg, bf16x8& pa0, bf16x8& pa1, bf16x8& pa2, bf16x8& pa3) {
;   for (int r = 0; r < 16; ++r) p1[r] = __builtin_amdgcn_exp2f(p1[r]);
;   float ps = 0; for (int r = 0; r < 16; ++r) ps += p0[r]; for (int r = 0; r < 16; ++r) ps += p1[r];
;   { auto rr = __builtin_amdgcn_permlane32_swap(__float_as_uint(ps), __float_as_uint(ps), false, false);
;     ps = __uint_as_float(rr[0]) + __uint_as_float(rr[1]); }
;   l_reg = l_reg * alpha + ps;
;     ...
;   PK4(p0, 0, pa0); PK4(p0, 8, pa1); PK4(p1, 0, pa2); PK4(p1, 8, pa3);
; __device__ __forceinline__ void attn_body(const u16* __restrict__ Qb, const u16* __restrict__ Kh, const u16* __restrict__ Vh,
;                                           u16* __restrict__ Ob, int seq, int wvs) {
;     ...
;   TBAR(2);
;   SBAR(); qkt(pB0, pB1, K_lds + sK * SHM_K, qr, r32, hi);
;   finishSM(pA0, pA1, alA, l_reg, pa0, pa1, pa2, pa3); SBAR();
;   pv_d0(o, vb0 + sV * SHM_V, pa0, pa1, pa2, pa3); partialSM(pB0, pB1, m_reg, mnB, alB);
.LBB0_372:
	s_waitcnt vmcnt(2) lgkmcnt(0)
	s_barrier
	s_mul_i32 s4, s31, 0x6000
	s_add_i32 s4, s4, 0
	v_add_u32_e32 v68, s4, v193
	ds_read_b128 v[64:67], v68 offset:49152
	ds_read_b128 v[68:71], v68 offset:61440
	v_add_u32_e32 v162, s4, v199
	s_waitcnt lgkmcnt(0)
	v_mfma_f32_32x32x16_bf16 v[80:95], v[64:67], v[140:143], 0
	v_mfma_f32_32x32x16_bf16 v[64:79], v[68:71], v[140:143], 0
	ds_read_b128 v[140:143], v162 offset:49152
	ds_read_b128 v[166:169], v162 offset:61440
	s_waitcnt lgkmcnt(0)
	v_mfma_f32_32x32x16_bf16 v[80:95], v[140:143], v[136:139], v[80:95]
	v_add_u32_e32 v140, s4, v200
	v_mfma_f32_32x32x16_bf16 v[64:79], v[166:169], v[136:139], v[64:79]
	ds_read_b128 v[136:139], v140 offset:49152
	ds_read_b128 v[140:143], v140 offset:61440
	s_waitcnt lgkmcnt(0)
	v_mfma_f32_32x32x16_bf16 v[80:95], v[136:139], v[132:135], v[80:95]
	v_add_u32_e32 v136, s4, v202
	v_mfma_f32_32x32x16_bf16 v[64:79], v[140:143], v[132:135], v[64:79]
	ds_read_b128 v[132:135], v136 offset:49152
	ds_read_b128 v[136:139], v136 offset:61440
	s_waitcnt lgkmcnt(0)
	v_mfma_f32_32x32x16_bf16 v[80:95], v[132:135], v[128:131], v[80:95]
	v_add_u32_e32 v132, s4, v207
	v_mfma_f32_32x32x16_bf16 v[64:79], v[136:139], v[128:131], v[64:79]
	ds_read_b128 v[128:131], v132 offset:49152
	ds_read_b128 v[132:135], v132 offset:61440
	s_waitcnt lgkmcnt(0)
	v_mfma_f32_32x32x16_bf16 v[80:95], v[128:131], v[124:127], v[80:95]
	v_add_u32_e32 v128, s4, v203
	v_mfma_f32_32x32x16_bf16 v[64:79], v[132:135], v[124:127], v[64:79]
	ds_read_b128 v[124:127], v128 offset:49152
	ds_read_b128 v[128:131], v128 offset:61440
	s_waitcnt lgkmcnt(0)
	v_mfma_f32_32x32x16_bf16 v[80:95], v[124:127], v[120:123], v[80:95]
	v_add_u32_e32 v124, s4, v201
	v_mfma_f32_32x32x16_bf16 v[64:79], v[128:131], v[120:123], v[64:79]
	ds_read_b128 v[120:123], v124 offset:49152
	ds_read_b128 v[124:127], v124 offset:61440
	s_waitcnt lgkmcnt(0)
	v_mfma_f32_32x32x16_bf16 v[80:95], v[120:123], v[116:119], v[80:95]
	v_add_u32_e32 v120, s4, v198
	v_mfma_f32_32x32x16_bf16 v[64:79], v[124:127], v[116:119], v[64:79]
	ds_read_b128 v[116:119], v120 offset:49152
	ds_read_b128 v[120:123], v120 offset:61440
	s_waitcnt lgkmcnt(0)
	v_mfma_f32_32x32x16_bf16 v[80:95], v[116:119], v[112:115], v[80:95]
	v_add_u32_e32 v116, s4, v197
	v_mfma_f32_32x32x16_bf16 v[64:79], v[120:123], v[112:115], v[64:79]
	ds_read_b128 v[112:115], v116 offset:49152
	ds_read_b128 v[116:119], v116 offset:61440
	v_exp_f32_e32 v120, v144
	v_exp_f32_e32 v121, v145
	s_waitcnt lgkmcnt(0)
	v_mfma_f32_32x32x16_bf16 v[80:95], v[112:115], v[108:111], v[80:95]
	v_add_u32_e32 v112, s4, v196
	v_mfma_f32_32x32x16_bf16 v[64:79], v[116:119], v[108:111], v[64:79]
	ds_read_b128 v[108:111], v112 offset:49152
	ds_read_b128 v[112:115], v112 offset:61440
	v_exp_f32_e32 v116, v148
	v_exp_f32_e32 v117, v149
	v_exp_f32_e32 v118, v146
	v_exp_f32_e32 v119, v147
	s_waitcnt lgkmcnt(0)
	v_mfma_f32_32x32x16_bf16 v[80:95], v[108:111], v[104:107], v[80:95]
	v_add_u32_e32 v108, s4, v195
	v_mfma_f32_32x32x16_bf16 v[64:79], v[112:115], v[104:107], v[64:79]
	ds_read_b128 v[104:107], v108 offset:49152
	ds_read_b128 v[108:111], v108 offset:61440
	v_exp_f32_e32 v114, v150
	v_exp_f32_e32 v115, v151
	s_waitcnt lgkmcnt(0)
	v_mfma_f32_32x32x16_bf16 v[80:95], v[104:107], v[100:103], v[80:95]
	v_add_u32_e32 v104, s4, v194
	v_mfma_f32_32x32x16_bf16 v[64:79], v[108:111], v[100:103], v[64:79]
	ds_read_b128 v[100:103], v104 offset:49152
	ds_read_b128 v[104:107], v104 offset:61440
	v_exp_f32_e32 v108, v154
	v_exp_f32_e32 v109, v155
	v_exp_f32_e32 v110, v152
	v_exp_f32_e32 v111, v153
	s_waitcnt lgkmcnt(0)
	v_mfma_f32_32x32x16_bf16 v[80:95], v[100:103], v[96:99], v[80:95]
	v_cvt_pk_bf16_f32 v100, v211, v212
	v_cvt_pk_bf16_f32 v101, v213, v215
	v_cvt_pk_bf16_f32 v102, v214, v216
	v_cvt_pk_bf16_f32 v103, v217, v219
	s_nop 0
	v_mfma_f32_32x32x16_bf16 v[64:79], v[104:107], v[96:99], v[64:79]
	v_add_f32_e32 v96, 0, v218
	v_add_f32_e32 v96, v220, v96
	v_add_f32_e32 v96, v221, v96
	v_add_f32_e32 v96, v222, v96
	v_add_f32_e32 v96, v223, v96
	v_add_f32_e32 v96, v225, v96
	v_add_f32_e32 v96, v224, v96
	v_add_f32_e32 v96, v226, v96
	v_add_f32_e32 v96, v211, v96
	v_add_f32_e32 v96, v212, v96
	v_add_f32_e32 v96, v213, v96
	v_add_f32_e32 v96, v215, v96
	v_exp_f32_e32 v104, v158
	v_add_f32_e32 v96, v214, v96
	v_exp_f32_e32 v105, v159
	v_add_f32_e32 v96, v216, v96
	v_exp_f32_e32 v106, v156
	v_add_f32_e32 v96, v217, v96
	v_exp_f32_e32 v107, v157
	v_add_f32_e32 v96, v219, v96
	v_add_f32_e32 v96, v104, v96
	v_add_f32_e32 v96, v105, v96
	v_add_f32_e32 v96, v106, v96
	v_add_f32_e32 v96, v107, v96
	v_add_f32_e32 v96, v108, v96
	v_add_f32_e32 v96, v109, v96
	v_add_f32_e32 v96, v110, v96
	v_add_f32_e32 v96, v111, v96
	v_add_f32_e32 v96, v114, v96
	v_add_f32_e32 v96, v115, v96
	v_add_f32_e32 v96, v116, v96
	v_add_f32_e32 v96, v117, v96
	v_add_f32_e32 v96, v118, v96
	v_add_f32_e32 v96, v119, v96
	v_add_f32_e32 v96, v120, v96
	v_add_f32_e32 v112, v121, v96
	v_mov_b32_e32 v113, v112
	v_cvt_pk_bf16_f32 v96, v218, v220
	v_cvt_pk_bf16_f32 v97, v221, v222
	v_cvt_pk_bf16_f32 v98, v223, v225
	v_cvt_pk_bf16_f32 v99, v224, v226
	v_permlane32_swap_b32_e32 v112, v113
	v_cvt_pk_bf16_f32 v104, v104, v105
	v_cvt_pk_bf16_f32 v105, v106, v107
	v_cvt_pk_bf16_f32 v106, v108, v109
	v_cvt_pk_bf16_f32 v107, v110, v111
	v_cvt_pk_bf16_f32 v108, v114, v115
	v_cvt_pk_bf16_f32 v109, v116, v117
	v_cvt_pk_bf16_f32 v110, v118, v119
	v_cvt_pk_bf16_f32 v111, v120, v121
	v_add_u32_e32 v130, s17, v190
	ds_read_b64_tr_b16 v[114:115], v130
	ds_read_b64_tr_b16 v[116:117], v130 offset:2048
	ds_read_b64_tr_b16 v[118:119], v130 offset:4096
	ds_read_b64_tr_b16 v[120:121], v130 offset:6144
	ds_read_b64_tr_b16 v[122:123], v130 offset:8192
	ds_read_b64_tr_b16 v[124:125], v130 offset:10240
	ds_read_b64_tr_b16 v[126:127], v130 offset:12288
	ds_read_b64_tr_b16 v[128:129], v130 offset:14336
	s_waitcnt lgkmcnt(0)
; #define RESC(a) do { if (__any((a) < 1.f)) { if (hi == 0) al_l[r32] = (a); asm volatile("s_waitcnt lgkmcnt(0)" ::: "memory"); \
;     for (int d = 0; d < 4; ++d) for (int r = 0; r < 16; ++r) o[d][r] *= al_l[crow(r, hi)]; } } while (0)
; __device__ __forceinline__ void partialSM(f32x16& p0, f32x16& p1, float& m_reg, float& mn, float& alpha) {
;   constexpr float C = ASCALE * 1.4426950408889634f;
;   float pmax = p0[0]; for (int r = 1; r < 16; ++r) pmax = fmaxf(pmax, p0[r]); for (int r = 0; r < 16; ++r) pmax = fmaxf(pmax, p1[r]);
;   { auto rr = __builtin_amdgcn_permlane32_swap(__float_as_uint(pmax), __float_as_uint(pmax), false, false);
;     pmax = fmaxf(__uint_as_float(rr[0]), __uint_as_float(rr[1])); }
;   if (__builtin_expect(__all(pmax - m_reg <= THR / ASCALE), 1)) { mn = m_reg; alpha = 1.f; }
;   else { mn = fmaxf(m_reg, pmax); alpha = __builtin_amdgcn_exp2f((m_reg - mn) * C); m_reg = mn; }
; __device__ __forceinline__ void attn_body(const u16* __restrict__ Qb, const u16* __restrict__ Kh, const u16* __restrict__ Vh,
;                                           u16* __restrict__ Ob, int seq, int wvs) {
;     ...
;   pv_d0(o, vb0 + sV * SHM_V, pa0, pa1, pa2, pa3); partialSM(pB0, pB1, m_reg, mnB, alB);
;   RESC(alB);
	v_mfma_f32_32x32x16_bf16 v[0:15], v[96:99], v[114:117], v[0:15]
	v_mfma_f32_32x32x16_bf16 v[0:15], v[100:103], v[118:121], v[0:15]
	v_mfma_f32_32x32x16_bf16 v[0:15], v[104:107], v[122:125], v[0:15]
	v_mfma_f32_32x32x16_bf16 v[0:15], v[108:111], v[126:129], v[0:15]
	ds_read_b64_tr_b16 v[114:115], v130 offset:512
	ds_read_b64_tr_b16 v[116:117], v130 offset:2560
	ds_read_b64_tr_b16 v[118:119], v130 offset:4608
	ds_read_b64_tr_b16 v[120:121], v130 offset:6656
	ds_read_b64_tr_b16 v[122:123], v130 offset:8704
	ds_read_b64_tr_b16 v[124:125], v130 offset:10752
	ds_read_b64_tr_b16 v[126:127], v130 offset:12800
	ds_read_b64_tr_b16 v[128:129], v130 offset:14848
	s_waitcnt lgkmcnt(0)
	v_mfma_f32_32x32x16_bf16 v[48:63], v[96:99], v[114:117], v[48:63]
	v_mfma_f32_32x32x16_bf16 v[48:63], v[100:103], v[118:121], v[48:63]
	v_mfma_f32_32x32x16_bf16 v[48:63], v[104:107], v[122:125], v[48:63]
	v_mfma_f32_32x32x16_bf16 v[48:63], v[108:111], v[126:129], v[48:63]
	ds_read_b64_tr_b16 v[114:115], v130 offset:1024
	ds_read_b64_tr_b16 v[116:117], v130 offset:3072
	ds_read_b64_tr_b16 v[118:119], v130 offset:5120
	ds_read_b64_tr_b16 v[120:121], v130 offset:7168
	ds_read_b64_tr_b16 v[122:123], v130 offset:9216
	ds_read_b64_tr_b16 v[124:125], v130 offset:11264
	ds_read_b64_tr_b16 v[126:127], v130 offset:13312
	ds_read_b64_tr_b16 v[128:129], v130 offset:15360
	s_waitcnt lgkmcnt(0)
	v_mfma_f32_32x32x16_bf16 v[32:47], v[96:99], v[114:117], v[32:47]
	v_mfma_f32_32x32x16_bf16 v[32:47], v[100:103], v[118:121], v[32:47]
	v_mfma_f32_32x32x16_bf16 v[32:47], v[104:107], v[122:125], v[32:47]
	v_mfma_f32_32x32x16_bf16 v[32:47], v[108:111], v[126:129], v[32:47]
	ds_read_b64_tr_b16 v[114:115], v130 offset:1536
	ds_read_b64_tr_b16 v[116:117], v130 offset:3584
	ds_read_b64_tr_b16 v[118:119], v130 offset:5632
	ds_read_b64_tr_b16 v[120:121], v130 offset:7680
	ds_read_b64_tr_b16 v[122:123], v130 offset:9728
	ds_read_b64_tr_b16 v[124:125], v130 offset:11776
	ds_read_b64_tr_b16 v[126:127], v130 offset:13824
	ds_read_b64_tr_b16 v[128:129], v130 offset:15872
	s_waitcnt lgkmcnt(0)
	v_mfma_f32_32x32x16_bf16 v[16:31], v[96:99], v[114:117], v[16:31]
	v_max_f32_e32 v96, v80, v81
	v_max3_f32 v96, v96, v82, v83
	v_max3_f32 v96, v96, v84, v85
	v_max3_f32 v96, v96, v86, v87
	v_max3_f32 v96, v96, v88, v89
	v_max3_f32 v96, v96, v90, v91
	v_max3_f32 v96, v96, v92, v93
	v_mfma_f32_32x32x16_bf16 v[16:31], v[100:103], v[118:121], v[16:31]
	v_max3_f32 v96, v96, v94, v95
	v_max3_f32 v96, v96, v64, v65
	v_max3_f32 v96, v96, v66, v67
	v_max3_f32 v96, v96, v68, v69
	v_max3_f32 v96, v96, v70, v71
	v_max3_f32 v96, v96, v72, v73
	v_max3_f32 v96, v96, v74, v75
	v_max3_f32 v96, v96, v76, v77
	v_mfma_f32_32x32x16_bf16 v[16:31], v[104:107], v[122:125], v[16:31]
	v_max3_f32 v96, v96, v78, v79
	v_mov_b32_e32 v97, v96
	s_nop 1
	v_permlane32_swap_b32_e32 v96, v97
	v_max_f32_e32 v96, v96, v97
	v_sub_f32_e32 v97, v96, v191
	v_cmp_ge_f32_e32 vcc, s35, v97
	v_max_f32_e32 v97, v191, v191
	v_max_f32_e32 v97, v97, v96
	v_mfma_f32_32x32x16_bf16 v[16:31], v[108:111], v[126:129], v[16:31]
	v_sub_f32_e32 v96, v191, v97
	v_mul_f32_e32 v96, 0x3dd53b94, v96
	v_exp_f32_e32 v96, v96
	s_cmp_eq_u64 vcc, exec
	s_cselect_b64 s[8:9], -1, 0
	v_cndmask_b32_e64 v96, v96, 1.0, s[8:9]
	v_cmp_gt_f32_e32 vcc, 1.0, v96
	s_cbranch_vccz .LBB0_376
	s_and_saveexec_b64 s[4:5], s[6:7]
	ds_write_b32 v188, v96 offset:128
	s_or_b64 exec, exec, s[4:5]
	s_waitcnt lgkmcnt(0)
	v_add_u32_e32 v110, v165, v160
	ds_read_b128 v[98:101], v110 offset:224
	ds_read_b128 v[102:105], v110 offset:192
	ds_read_b128 v[106:109], v110 offset:160
	ds_read_b128 v[114:117], v110 offset:128
	s_waitcnt lgkmcnt(0)
	v_pk_mul_f32 v[12:13], v[12:13], v[98:99]
	v_pk_mul_f32 v[8:9], v[8:9], v[102:103]
	v_pk_mul_f32 v[4:5], v[4:5], v[106:107]
	v_pk_mul_f32 v[14:15], v[14:15], v[100:101]
	v_pk_mul_f32 v[10:11], v[10:11], v[104:105]
	v_pk_mul_f32 v[6:7], v[6:7], v[108:109]
	v_pk_mul_f32 v[2:3], v[2:3], v[116:117]
	v_pk_mul_f32 v[0:1], v[0:1], v[114:115]
	v_pk_mul_f32 v[60:61], v[60:61], v[98:99]
	v_pk_mul_f32 v[56:57], v[56:57], v[102:103]
	v_pk_mul_f32 v[52:53], v[52:53], v[106:107]
	v_pk_mul_f32 v[62:63], v[62:63], v[100:101]
	v_pk_mul_f32 v[58:59], v[58:59], v[104:105]
	v_pk_mul_f32 v[54:55], v[54:55], v[108:109]
	v_pk_mul_f32 v[50:51], v[50:51], v[116:117]
	v_pk_mul_f32 v[48:49], v[48:49], v[114:115]
	v_pk_mul_f32 v[44:45], v[44:45], v[98:99]
	v_pk_mul_f32 v[40:41], v[40:41], v[102:103]
	v_pk_mul_f32 v[36:37], v[36:37], v[106:107]
	v_pk_mul_f32 v[46:47], v[46:47], v[100:101]
	v_pk_mul_f32 v[42:43], v[42:43], v[104:105]
	v_pk_mul_f32 v[38:39], v[38:39], v[108:109]
	v_pk_mul_f32 v[34:35], v[34:35], v[116:117]
	v_pk_mul_f32 v[32:33], v[32:33], v[114:115]
	v_pk_mul_f32 v[28:29], v[28:29], v[98:99]
	v_pk_mul_f32 v[24:25], v[24:25], v[102:103]
	v_pk_mul_f32 v[20:21], v[20:21], v[106:107]
	v_pk_mul_f32 v[30:31], v[30:31], v[100:101]
	v_pk_mul_f32 v[26:27], v[26:27], v[104:105]
	v_pk_mul_f32 v[22:23], v[22:23], v[108:109]
	v_pk_mul_f32 v[18:19], v[18:19], v[116:117]
	v_pk_mul_f32 v[16:17], v[16:17], v[114:115]
